# FFN-in epilogue: quad-pair v_permlane16_swap, one dwordx4 store per row block instead of two dwordx2
# speedup vs baseline: 1.0231x; 1.0034x over previous
.LBB0_673:
	v_add3_u32 v132, v136, v137, s52
	ds_read_b128 v[128:131], v132
	ds_read_b128 v[138:141], v132 offset:2048
	ds_read_b128 v[154:157], v132 offset:4096
	ds_read_b128 v[158:161], v132 offset:6144
	v_add3_u32 v132, v134, v137, s81
	ds_read_b128 v[162:165], v132
	ds_read_b128 v[166:169], v132 offset:2048
	ds_read_b128 v[170:173], v132 offset:4096
	ds_read_b128 v[174:177], v132 offset:6144
	ds_read_b128 v[178:181], v132 offset:8192
	ds_read_b128 v[182:185], v132 offset:10240
	ds_read_b128 v[186:189], v132 offset:12288
	ds_read_b128 v[216:219], v132 offset:14336
	s_waitcnt lgkmcnt(0)
	v_mfma_f32_16x16x32_bf16 v[116:119], v[128:131], v[162:165], v[116:119]
	v_mfma_f32_16x16x32_bf16 v[108:111], v[138:141], v[162:165], v[108:111]
	v_mfma_f32_16x16x32_bf16 v[100:103], v[154:157], v[162:165], v[100:103]
	v_mfma_f32_16x16x32_bf16 v[88:91], v[158:161], v[162:165], v[88:91]
	v_mfma_f32_16x16x32_bf16 v[76:79], v[128:131], v[166:169], v[76:79]
	v_mfma_f32_16x16x32_bf16 v[68:71], v[138:141], v[166:169], v[68:71]
	v_mfma_f32_16x16x32_bf16 v[56:59], v[154:157], v[166:169], v[56:59]
	v_mfma_f32_16x16x32_bf16 v[44:47], v[158:161], v[166:169], v[44:47]
	v_mfma_f32_16x16x32_bf16 v[36:39], v[128:131], v[170:173], v[36:39]
	v_mfma_f32_16x16x32_bf16 v[32:35], v[138:141], v[170:173], v[32:35]
	v_mfma_f32_16x16x32_bf16 v[28:31], v[154:157], v[170:173], v[28:31]
	v_mfma_f32_16x16x32_bf16 v[24:27], v[158:161], v[170:173], v[24:27]
	v_mfma_f32_16x16x32_bf16 v[20:23], v[128:131], v[174:177], v[20:23]
	v_mfma_f32_16x16x32_bf16 v[16:19], v[138:141], v[174:177], v[16:19]
	v_mfma_f32_16x16x32_bf16 v[12:15], v[154:157], v[174:177], v[12:15]
	v_mfma_f32_16x16x32_bf16 v[8:11], v[158:161], v[174:177], v[8:11]
	v_add3_u32 v132, v136, v135, s52
	v_add3_u32 v144, v134, v135, s81
	ds_read_b128 v[162:165], v132
	ds_read_b128 v[166:169], v132 offset:2048
	ds_read_b128 v[170:173], v132 offset:4096
	ds_read_b128 v[174:177], v132 offset:6144
	ds_read_b128 v[132:135], v144
	ds_read_b128 v[220:223], v144 offset:2048
	ds_read_b128 v[224:227], v144 offset:4096
	ds_read_b128 v[228:231], v144 offset:6144
	v_mfma_f32_16x16x32_bf16 v[4:7], v[128:131], v[178:181], v[4:7]
	v_mfma_f32_16x16x32_bf16 v[0:3], v[138:141], v[178:181], v[0:3]
	v_mfma_f32_16x16x32_bf16 v[40:43], v[154:157], v[178:181], v[40:43]
	v_mfma_f32_16x16x32_bf16 v[48:51], v[158:161], v[178:181], v[48:51]
	v_mfma_f32_16x16x32_bf16 v[178:181], v[128:131], v[182:185], v[52:55]
	v_mfma_f32_16x16x32_bf16 v[232:235], v[138:141], v[182:185], v[60:63]
	v_mfma_f32_16x16x32_bf16 v[236:239], v[154:157], v[182:185], v[64:67]
	v_mfma_f32_16x16x32_bf16 v[182:185], v[158:161], v[182:185], v[72:75]
	v_mfma_f32_16x16x32_bf16 v[240:243], v[128:131], v[186:189], v[80:83]
	v_mfma_f32_16x16x32_bf16 v[244:247], v[138:141], v[186:189], v[84:87]
	v_mfma_f32_16x16x32_bf16 v[248:251], v[154:157], v[186:189], v[92:95]
	v_mfma_f32_16x16x32_bf16 v[186:189], v[158:161], v[186:189], v[96:99]
	v_mfma_f32_16x16x32_bf16 v[128:131], v[128:131], v[216:219], v[104:107]
	v_mfma_f32_16x16x32_bf16 v[136:139], v[138:141], v[216:219], v[112:115]
	v_mfma_f32_16x16x32_bf16 v[140:143], v[154:157], v[216:219], v[120:123]
	v_mfma_f32_16x16x32_bf16 v[154:157], v[158:161], v[216:219], v[124:127]
	ds_read_b128 v[158:161], v144 offset:8192
	ds_read_b128 v[216:219], v144 offset:10240
	ds_read_b128 v[146:149], v144 offset:12288
	ds_read_b128 v[206:209], v144 offset:14336
	s_waitcnt lgkmcnt(0)
	v_mfma_f32_16x16x32_bf16 v[124:127], v[162:165], v[132:135], v[116:119]
	v_mfma_f32_16x16x32_bf16 v[120:123], v[166:169], v[132:135], v[108:111]
	v_mfma_f32_16x16x32_bf16 v[116:119], v[170:173], v[132:135], v[100:103]
	v_mfma_f32_16x16x32_bf16 v[112:115], v[174:177], v[132:135], v[88:91]
	v_mfma_f32_16x16x32_bf16 v[108:111], v[162:165], v[220:223], v[76:79]
	v_mfma_f32_16x16x32_bf16 v[104:107], v[166:169], v[220:223], v[68:71]
	v_mfma_f32_16x16x32_bf16 v[100:103], v[170:173], v[220:223], v[56:59]
	v_mfma_f32_16x16x32_bf16 v[96:99], v[174:177], v[220:223], v[44:47]
	v_mfma_f32_16x16x32_bf16 v[92:95], v[162:165], v[224:227], v[36:39]
	v_mfma_f32_16x16x32_bf16 v[88:91], v[166:169], v[224:227], v[32:35]
	v_mfma_f32_16x16x32_bf16 v[84:87], v[170:173], v[224:227], v[28:31]
	v_mfma_f32_16x16x32_bf16 v[80:83], v[174:177], v[224:227], v[24:27]
	v_mfma_f32_16x16x32_bf16 v[76:79], v[162:165], v[228:231], v[20:23]
	v_mfma_f32_16x16x32_bf16 v[72:75], v[166:169], v[228:231], v[16:19]
	v_mfma_f32_16x16x32_bf16 v[68:71], v[170:173], v[228:231], v[12:15]
	v_mfma_f32_16x16x32_bf16 v[64:67], v[174:177], v[228:231], v[8:11]
	v_mfma_f32_16x16x32_bf16 v[60:63], v[162:165], v[158:161], v[4:7]
	s_lshl_b32 s0, s26, 8
	s_mov_b64 s[2:3], -1
	s_and_b64 vcc, exec, s[24:25]
	v_mfma_f32_16x16x32_bf16 v[56:59], v[166:169], v[158:161], v[0:3]
	v_mfma_f32_16x16x32_bf16 v[52:55], v[170:173], v[158:161], v[40:43]
	v_mfma_f32_16x16x32_bf16 v[48:51], v[174:177], v[158:161], v[48:51]
	v_mfma_f32_16x16x32_bf16 v[44:47], v[162:165], v[216:219], v[178:181]
	v_mfma_f32_16x16x32_bf16 v[40:43], v[166:169], v[216:219], v[232:235]
	v_mfma_f32_16x16x32_bf16 v[36:39], v[170:173], v[216:219], v[236:239]
	v_mfma_f32_16x16x32_bf16 v[32:35], v[174:177], v[216:219], v[182:185]
	v_mfma_f32_16x16x32_bf16 v[28:31], v[162:165], v[146:149], v[240:243]
	v_mfma_f32_16x16x32_bf16 v[24:27], v[166:169], v[146:149], v[244:247]
	v_mfma_f32_16x16x32_bf16 v[20:23], v[170:173], v[146:149], v[248:251]
	v_mfma_f32_16x16x32_bf16 v[16:19], v[174:177], v[146:149], v[186:189]
	v_mfma_f32_16x16x32_bf16 v[12:15], v[162:165], v[206:209], v[128:131]
	v_mfma_f32_16x16x32_bf16 v[8:11], v[166:169], v[206:209], v[136:139]
	v_mfma_f32_16x16x32_bf16 v[4:7], v[170:173], v[206:209], v[140:143]
	v_mfma_f32_16x16x32_bf16 v[0:3], v[174:177], v[206:209], v[154:157]
	s_cbranch_vccz .LBB0_675
	v_mov_b32_e32 v128, v190
	s_lshl_b32 s2, s22, 7
	v_ashrrev_i32_e32 v130, 1, v128
	v_and_b32_e32 v129, 15, v128
	v_and_b32_e32 v130, 0xffffff80, v130
	v_or_b32_e32 v131, s0, v129
	v_or_b32_e32 v129, v130, v129
	v_add_u32_e32 v131, v131, v130
	v_lshl_add_u32 v130, v129, 2, v205
	ds_read_b32 v136, v130
	s_ashr_i32 s3, s2, 31
	s_lshl_b64 s[2:3], s[2:3], 1
	s_add_u32 s2, s66, s2
	s_addc_u32 s3, s67, s3
	s_waitcnt lgkmcnt(0)
	v_mul_f32_e32 v134, v124, v136
	v_mul_f32_e32 v135, 0xbfb8aa3b, v134
	v_exp_f32_e32 v135, v135
	v_lshrrev_b32_e32 v132, 1, v128
	v_and_b32_e32 v144, 0xc0, v128
	v_lshl_add_u64 v[128:129], s[2:3], 0, v[144:145]
	v_add_f32_e32 v135, 1.0, v135
	v_rcp_f32_e32 v135, v135
	v_and_b32_e32 v144, 24, v132
	v_lshl_add_u64 v[128:129], v[128:129], 0, v[144:145]
	v_and_b32_e32 v144, 8, v144
	v_mul_u32_u24_e32 v144, 3, v144
	v_lshl_add_u64 v[128:129], v[128:129], 0, v[144:145]
	v_mad_i64_i32 v[132:133], s[2:3], v131, s33, v[128:129]
	v_mul_f32_e32 v134, v134, v135
	v_mul_f32_e32 v135, v120, v136
	v_mul_f32_e32 v134, v135, v134
	v_mul_f32_e32 v135, v125, v136
	v_mul_f32_e32 v137, 0xbfb8aa3b, v135
	v_exp_f32_e32 v137, v137
	s_nop 0
	v_add_f32_e32 v137, 1.0, v137
	v_rcp_f32_e32 v137, v137
	s_nop 0
	v_mul_f32_e32 v135, v135, v137
	v_mul_f32_e32 v137, v121, v136
	v_mul_f32_e32 v135, v137, v135
	v_mul_f32_e32 v137, v126, v136
	v_mul_f32_e32 v138, 0xbfb8aa3b, v137
	v_exp_f32_e32 v138, v138
	v_cvt_pk_bf16_f32 v134, v134, v135
	s_nop 0
	v_add_f32_e32 v138, 1.0, v138
	v_rcp_f32_e32 v138, v138
	s_nop 0
	v_mul_f32_e32 v137, v137, v138
	v_mul_f32_e32 v138, v122, v136
	v_mul_f32_e32 v137, v138, v137
	v_mul_f32_e32 v138, v127, v136
	v_mul_f32_e32 v139, 0xbfb8aa3b, v138
	v_exp_f32_e32 v139, v139
	s_nop 0
	v_add_f32_e32 v139, 1.0, v139
	v_rcp_f32_e32 v139, v139
	s_nop 0
	v_mul_f32_e32 v138, v138, v139
	v_mul_f32_e32 v139, v123, v136
	v_mul_f32_e32 v138, v139, v138
	v_cvt_pk_bf16_f32 v135, v137, v138
	s_waitcnt vmcnt(0)
	v_mov_b32_e32 v248, v134
	v_mov_b32_e32 v249, v135
	v_mul_f32_e32 v134, v116, v136
	v_mul_f32_e32 v135, 0xbfb8aa3b, v134
	v_exp_f32_e32 v135, v135
	s_nop 0
	v_add_f32_e32 v135, 1.0, v135
	v_rcp_f32_e32 v135, v135
	s_nop 0
	v_mul_f32_e32 v134, v134, v135
	v_mul_f32_e32 v135, v112, v136
	v_mul_f32_e32 v134, v135, v134
	v_mul_f32_e32 v135, v117, v136
	v_mul_f32_e32 v137, 0xbfb8aa3b, v135
	v_exp_f32_e32 v137, v137
	s_nop 0
	v_add_f32_e32 v137, 1.0, v137
	v_rcp_f32_e32 v137, v137
	s_nop 0
	v_mul_f32_e32 v135, v135, v137
	v_mul_f32_e32 v137, v113, v136
	v_mul_f32_e32 v135, v137, v135
	v_mul_f32_e32 v137, v118, v136
	v_mul_f32_e32 v138, 0xbfb8aa3b, v137
	v_exp_f32_e32 v138, v138
	v_cvt_pk_bf16_f32 v134, v134, v135
	s_nop 0
	v_add_f32_e32 v138, 1.0, v138
	v_rcp_f32_e32 v138, v138
	s_nop 0
	v_mul_f32_e32 v137, v137, v138
	v_mul_f32_e32 v138, v114, v136
	v_mul_f32_e32 v137, v138, v137
	v_mul_f32_e32 v138, v119, v136
	v_mul_f32_e32 v139, 0xbfb8aa3b, v138
	v_exp_f32_e32 v139, v139
	v_mul_f32_e32 v136, v115, v136
	v_add_f32_e32 v139, 1.0, v139
	v_rcp_f32_e32 v139, v139
	s_nop 0
	v_mul_f32_e32 v138, v138, v139
	v_mul_f32_e32 v136, v136, v138
	v_cvt_pk_bf16_f32 v135, v137, v136
	v_mov_b32_e32 v250, v134
	v_mov_b32_e32 v251, v135
	s_nop 1
	v_permlane16_swap_b32 v248, v250
	v_permlane16_swap_b32 v249, v251
	flat_store_dwordx4 v[132:133], v[248:251]
	ds_read_b32 v136, v130 offset:64
	v_or_b32_e32 v132, 16, v131
	v_mad_i64_i32 v[132:133], s[2:3], v132, s33, v[128:129]
	s_waitcnt lgkmcnt(0)
	v_mul_f32_e32 v134, v108, v136
	v_mul_f32_e32 v135, 0xbfb8aa3b, v134
	v_exp_f32_e32 v135, v135
	s_nop 0
	v_add_f32_e32 v135, 1.0, v135
	v_rcp_f32_e32 v135, v135
	s_nop 0
	v_mul_f32_e32 v134, v134, v135
	v_mul_f32_e32 v135, v104, v136
	v_mul_f32_e32 v134, v135, v134
	v_mul_f32_e32 v135, v109, v136
	v_mul_f32_e32 v137, 0xbfb8aa3b, v135
	v_exp_f32_e32 v137, v137
	s_nop 0
	v_add_f32_e32 v137, 1.0, v137
	v_rcp_f32_e32 v137, v137
	s_nop 0
	v_mul_f32_e32 v135, v135, v137
	v_mul_f32_e32 v137, v105, v136
	v_mul_f32_e32 v135, v137, v135
	v_mul_f32_e32 v137, v110, v136
	v_mul_f32_e32 v138, 0xbfb8aa3b, v137
	v_exp_f32_e32 v138, v138
	v_cvt_pk_bf16_f32 v134, v134, v135
	s_nop 0
	v_add_f32_e32 v138, 1.0, v138
	v_rcp_f32_e32 v138, v138
	s_nop 0
	v_mul_f32_e32 v137, v137, v138
	v_mul_f32_e32 v138, v106, v136
	v_mul_f32_e32 v137, v138, v137
	v_mul_f32_e32 v138, v111, v136
	v_mul_f32_e32 v139, 0xbfb8aa3b, v138
	v_exp_f32_e32 v139, v139
	s_nop 0
	v_add_f32_e32 v139, 1.0, v139
	v_rcp_f32_e32 v139, v139
	s_nop 0
	v_mul_f32_e32 v138, v138, v139
	v_mul_f32_e32 v139, v107, v136
	v_mul_f32_e32 v138, v139, v138
	v_cvt_pk_bf16_f32 v135, v137, v138
	v_mov_b32_e32 v248, v134
	v_mov_b32_e32 v249, v135
	v_mul_f32_e32 v134, v100, v136
	v_mul_f32_e32 v135, 0xbfb8aa3b, v134
	v_exp_f32_e32 v135, v135
	s_nop 0
	v_add_f32_e32 v135, 1.0, v135
	v_rcp_f32_e32 v135, v135
	s_nop 0
	v_mul_f32_e32 v134, v134, v135
	v_mul_f32_e32 v135, v96, v136
	v_mul_f32_e32 v134, v135, v134
	v_mul_f32_e32 v135, v101, v136
	v_mul_f32_e32 v137, 0xbfb8aa3b, v135
	v_exp_f32_e32 v137, v137
	s_nop 0
	v_add_f32_e32 v137, 1.0, v137
	v_rcp_f32_e32 v137, v137
	s_nop 0
	v_mul_f32_e32 v135, v135, v137
	v_mul_f32_e32 v137, v97, v136
	v_mul_f32_e32 v135, v137, v135
	v_mul_f32_e32 v137, v102, v136
	v_mul_f32_e32 v138, 0xbfb8aa3b, v137
	v_exp_f32_e32 v138, v138
	v_cvt_pk_bf16_f32 v134, v134, v135
	s_nop 0
	v_add_f32_e32 v138, 1.0, v138
	v_rcp_f32_e32 v138, v138
	s_nop 0
	v_mul_f32_e32 v137, v137, v138
	v_mul_f32_e32 v138, v98, v136
	v_mul_f32_e32 v137, v138, v137
	v_mul_f32_e32 v138, v103, v136
	v_mul_f32_e32 v139, 0xbfb8aa3b, v138
	v_exp_f32_e32 v139, v139
	v_mul_f32_e32 v136, v99, v136
	v_add_f32_e32 v139, 1.0, v139
	v_rcp_f32_e32 v139, v139
	s_nop 0
	v_mul_f32_e32 v138, v138, v139
	v_mul_f32_e32 v136, v136, v138
	v_cvt_pk_bf16_f32 v135, v137, v136
	v_mov_b32_e32 v250, v134
	v_mov_b32_e32 v251, v135
	s_nop 1
	v_permlane16_swap_b32 v248, v250
	v_permlane16_swap_b32 v249, v251
	flat_store_dwordx4 v[132:133], v[248:251]
	ds_read_b32 v136, v130 offset:128
	v_or_b32_e32 v132, 32, v131
	v_mad_i64_i32 v[132:133], s[2:3], v132, s33, v[128:129]
	s_waitcnt lgkmcnt(0)
	v_mul_f32_e32 v134, v92, v136
	v_mul_f32_e32 v135, 0xbfb8aa3b, v134
	v_exp_f32_e32 v135, v135
	s_nop 0
	v_add_f32_e32 v135, 1.0, v135
	v_rcp_f32_e32 v135, v135
	s_nop 0
	v_mul_f32_e32 v134, v134, v135
	v_mul_f32_e32 v135, v88, v136
	v_mul_f32_e32 v134, v135, v134
	v_mul_f32_e32 v135, v93, v136
	v_mul_f32_e32 v137, 0xbfb8aa3b, v135
	v_exp_f32_e32 v137, v137
	s_nop 0
	v_add_f32_e32 v137, 1.0, v137
	v_rcp_f32_e32 v137, v137
	s_nop 0
	v_mul_f32_e32 v135, v135, v137
	v_mul_f32_e32 v137, v89, v136
	v_mul_f32_e32 v135, v137, v135
	v_mul_f32_e32 v137, v94, v136
	v_mul_f32_e32 v138, 0xbfb8aa3b, v137
	v_exp_f32_e32 v138, v138
	v_cvt_pk_bf16_f32 v134, v134, v135
	s_nop 0
	v_add_f32_e32 v138, 1.0, v138
	v_rcp_f32_e32 v138, v138
	s_nop 0
	v_mul_f32_e32 v137, v137, v138
	v_mul_f32_e32 v138, v90, v136
	v_mul_f32_e32 v137, v138, v137
	v_mul_f32_e32 v138, v95, v136
	v_mul_f32_e32 v139, 0xbfb8aa3b, v138
	v_exp_f32_e32 v139, v139
	s_nop 0
	v_add_f32_e32 v139, 1.0, v139
	v_rcp_f32_e32 v139, v139
	s_nop 0
	v_mul_f32_e32 v138, v138, v139
	v_mul_f32_e32 v139, v91, v136
	v_mul_f32_e32 v138, v139, v138
	v_cvt_pk_bf16_f32 v135, v137, v138
	v_mov_b32_e32 v248, v134
	v_mov_b32_e32 v249, v135
	v_mul_f32_e32 v134, v84, v136
	v_mul_f32_e32 v135, 0xbfb8aa3b, v134
	v_exp_f32_e32 v135, v135
	s_nop 0
	v_add_f32_e32 v135, 1.0, v135
	v_rcp_f32_e32 v135, v135
	s_nop 0
	v_mul_f32_e32 v134, v134, v135
	v_mul_f32_e32 v135, v80, v136
	v_mul_f32_e32 v134, v135, v134
	v_mul_f32_e32 v135, v85, v136
	v_mul_f32_e32 v137, 0xbfb8aa3b, v135
	v_exp_f32_e32 v137, v137
	s_nop 0
	v_add_f32_e32 v137, 1.0, v137
	v_rcp_f32_e32 v137, v137
	s_nop 0
	v_mul_f32_e32 v135, v135, v137
	v_mul_f32_e32 v137, v81, v136
	v_mul_f32_e32 v135, v137, v135
	v_mul_f32_e32 v137, v86, v136
	v_mul_f32_e32 v138, 0xbfb8aa3b, v137
	v_exp_f32_e32 v138, v138
	v_cvt_pk_bf16_f32 v134, v134, v135
	s_nop 0
	v_add_f32_e32 v138, 1.0, v138
	v_rcp_f32_e32 v138, v138
	s_nop 0
	v_mul_f32_e32 v137, v137, v138
	v_mul_f32_e32 v138, v82, v136
	v_mul_f32_e32 v137, v138, v137
	v_mul_f32_e32 v138, v87, v136
	v_mul_f32_e32 v139, 0xbfb8aa3b, v138
	v_exp_f32_e32 v139, v139
	v_mul_f32_e32 v136, v83, v136
	v_add_f32_e32 v139, 1.0, v139
	v_rcp_f32_e32 v139, v139
	s_nop 0
	v_mul_f32_e32 v138, v138, v139
	v_mul_f32_e32 v136, v136, v138
	v_cvt_pk_bf16_f32 v135, v137, v136
	v_mov_b32_e32 v250, v134
	v_mov_b32_e32 v251, v135
	s_nop 1
	v_permlane16_swap_b32 v248, v250
	v_permlane16_swap_b32 v249, v251
	flat_store_dwordx4 v[132:133], v[248:251]
	ds_read_b32 v136, v130 offset:192
	v_or_b32_e32 v132, 48, v131
	v_mad_i64_i32 v[132:133], s[2:3], v132, s33, v[128:129]
	s_waitcnt lgkmcnt(0)
	v_mul_f32_e32 v134, v76, v136
	v_mul_f32_e32 v135, 0xbfb8aa3b, v134
	v_exp_f32_e32 v135, v135
	s_nop 0
	v_add_f32_e32 v135, 1.0, v135
	v_rcp_f32_e32 v135, v135
	s_nop 0
	v_mul_f32_e32 v134, v134, v135
	v_mul_f32_e32 v135, v72, v136
	v_mul_f32_e32 v134, v135, v134
	v_mul_f32_e32 v135, v77, v136
	v_mul_f32_e32 v137, 0xbfb8aa3b, v135
	v_exp_f32_e32 v137, v137
	s_nop 0
	v_add_f32_e32 v137, 1.0, v137
	v_rcp_f32_e32 v137, v137
	s_nop 0
	v_mul_f32_e32 v135, v135, v137
	v_mul_f32_e32 v137, v73, v136
	v_mul_f32_e32 v135, v137, v135
	v_mul_f32_e32 v137, v78, v136
	v_mul_f32_e32 v138, 0xbfb8aa3b, v137
	v_exp_f32_e32 v138, v138
	v_cvt_pk_bf16_f32 v134, v134, v135
	s_nop 0
	v_add_f32_e32 v138, 1.0, v138
	v_rcp_f32_e32 v138, v138
	s_nop 0
	v_mul_f32_e32 v137, v137, v138
	v_mul_f32_e32 v138, v74, v136
	v_mul_f32_e32 v137, v138, v137
	v_mul_f32_e32 v138, v79, v136
	v_mul_f32_e32 v139, 0xbfb8aa3b, v138
	v_exp_f32_e32 v139, v139
	s_nop 0
	v_add_f32_e32 v139, 1.0, v139
	v_rcp_f32_e32 v139, v139
	s_nop 0
	v_mul_f32_e32 v138, v138, v139
	v_mul_f32_e32 v139, v75, v136
	v_mul_f32_e32 v138, v139, v138
	v_cvt_pk_bf16_f32 v135, v137, v138
	v_mov_b32_e32 v248, v134
	v_mov_b32_e32 v249, v135
	v_mul_f32_e32 v134, v68, v136
	v_mul_f32_e32 v135, 0xbfb8aa3b, v134
	v_exp_f32_e32 v135, v135
	s_nop 0
	v_add_f32_e32 v135, 1.0, v135
	v_rcp_f32_e32 v135, v135
	s_nop 0
	v_mul_f32_e32 v134, v134, v135
	v_mul_f32_e32 v135, v64, v136
	v_mul_f32_e32 v134, v135, v134
	v_mul_f32_e32 v135, v69, v136
	v_mul_f32_e32 v137, 0xbfb8aa3b, v135
	v_exp_f32_e32 v137, v137
	s_nop 0
	v_add_f32_e32 v137, 1.0, v137
	v_rcp_f32_e32 v137, v137
	s_nop 0
	v_mul_f32_e32 v135, v135, v137
	v_mul_f32_e32 v137, v65, v136
	v_mul_f32_e32 v135, v137, v135
	v_mul_f32_e32 v137, v70, v136
	v_mul_f32_e32 v138, 0xbfb8aa3b, v137
	v_exp_f32_e32 v138, v138
	v_cvt_pk_bf16_f32 v134, v134, v135
	s_nop 0
	v_add_f32_e32 v138, 1.0, v138
	v_rcp_f32_e32 v138, v138
	s_nop 0
	v_mul_f32_e32 v137, v137, v138
	v_mul_f32_e32 v138, v66, v136
	v_mul_f32_e32 v137, v138, v137
	v_mul_f32_e32 v138, v71, v136
	v_mul_f32_e32 v139, 0xbfb8aa3b, v138
	v_exp_f32_e32 v139, v139
	v_mul_f32_e32 v136, v67, v136
	v_add_f32_e32 v139, 1.0, v139
	v_rcp_f32_e32 v139, v139
	s_nop 0
	v_mul_f32_e32 v138, v138, v139
	v_mul_f32_e32 v136, v136, v138
	v_cvt_pk_bf16_f32 v135, v137, v136
	v_mov_b32_e32 v250, v134
	v_mov_b32_e32 v251, v135
	s_nop 1
	v_permlane16_swap_b32 v248, v250
	v_permlane16_swap_b32 v249, v251
	flat_store_dwordx4 v[132:133], v[248:251]
	ds_read_b32 v136, v130 offset:256
	v_or_b32_e32 v132, 64, v131
	v_mad_i64_i32 v[132:133], s[2:3], v132, s33, v[128:129]
	s_waitcnt lgkmcnt(0)
	v_mul_f32_e32 v134, v60, v136
	v_mul_f32_e32 v135, 0xbfb8aa3b, v134
	v_exp_f32_e32 v135, v135
	s_nop 0
	v_add_f32_e32 v135, 1.0, v135
	v_rcp_f32_e32 v135, v135
	s_nop 0
	v_mul_f32_e32 v134, v134, v135
	v_mul_f32_e32 v135, v56, v136
	v_mul_f32_e32 v134, v135, v134
	v_mul_f32_e32 v135, v61, v136
	v_mul_f32_e32 v137, 0xbfb8aa3b, v135
	v_exp_f32_e32 v137, v137
	s_nop 0
	v_add_f32_e32 v137, 1.0, v137
	v_rcp_f32_e32 v137, v137
	s_nop 0
	v_mul_f32_e32 v135, v135, v137
	v_mul_f32_e32 v137, v57, v136
	v_mul_f32_e32 v135, v137, v135
	v_mul_f32_e32 v137, v62, v136
	v_mul_f32_e32 v138, 0xbfb8aa3b, v137
	v_exp_f32_e32 v138, v138
	v_cvt_pk_bf16_f32 v134, v134, v135
	s_nop 0
	v_add_f32_e32 v138, 1.0, v138
	v_rcp_f32_e32 v138, v138
	s_nop 0
	v_mul_f32_e32 v137, v137, v138
	v_mul_f32_e32 v138, v58, v136
	v_mul_f32_e32 v137, v138, v137
	v_mul_f32_e32 v138, v63, v136
	v_mul_f32_e32 v139, 0xbfb8aa3b, v138
	v_exp_f32_e32 v139, v139
	s_nop 0
	v_add_f32_e32 v139, 1.0, v139
	v_rcp_f32_e32 v139, v139
	s_nop 0
	v_mul_f32_e32 v138, v138, v139
	v_mul_f32_e32 v139, v59, v136
	v_mul_f32_e32 v138, v139, v138
	v_cvt_pk_bf16_f32 v135, v137, v138
	v_mov_b32_e32 v248, v134
	v_mov_b32_e32 v249, v135
	v_mul_f32_e32 v134, v52, v136
	v_mul_f32_e32 v135, 0xbfb8aa3b, v134
	v_exp_f32_e32 v135, v135
	s_nop 0
	v_add_f32_e32 v135, 1.0, v135
	v_rcp_f32_e32 v135, v135
	s_nop 0
	v_mul_f32_e32 v134, v134, v135
	v_mul_f32_e32 v135, v48, v136
	v_mul_f32_e32 v134, v135, v134
	v_mul_f32_e32 v135, v53, v136
	v_mul_f32_e32 v137, 0xbfb8aa3b, v135
	v_exp_f32_e32 v137, v137
	s_nop 0
	v_add_f32_e32 v137, 1.0, v137
	v_rcp_f32_e32 v137, v137
	s_nop 0
	v_mul_f32_e32 v135, v135, v137
	v_mul_f32_e32 v137, v49, v136
	v_mul_f32_e32 v135, v137, v135
	v_mul_f32_e32 v137, v54, v136
	v_mul_f32_e32 v138, 0xbfb8aa3b, v137
	v_exp_f32_e32 v138, v138
	v_cvt_pk_bf16_f32 v134, v134, v135
	s_nop 0
	v_add_f32_e32 v138, 1.0, v138
	v_rcp_f32_e32 v138, v138
	s_nop 0
	v_mul_f32_e32 v137, v137, v138
	v_mul_f32_e32 v138, v50, v136
	v_mul_f32_e32 v137, v138, v137
	v_mul_f32_e32 v138, v55, v136
	v_mul_f32_e32 v139, 0xbfb8aa3b, v138
	v_exp_f32_e32 v139, v139
	v_mul_f32_e32 v136, v51, v136
	v_add_f32_e32 v139, 1.0, v139
	v_rcp_f32_e32 v139, v139
	s_nop 0
	v_mul_f32_e32 v138, v138, v139
	v_mul_f32_e32 v136, v136, v138
	v_cvt_pk_bf16_f32 v135, v137, v136
	v_mov_b32_e32 v250, v134
	v_mov_b32_e32 v251, v135
	s_nop 1
	v_permlane16_swap_b32 v248, v250
	v_permlane16_swap_b32 v249, v251
	flat_store_dwordx4 v[132:133], v[248:251]
	ds_read_b32 v136, v130 offset:320
	v_or_b32_e32 v132, 0x50, v131
	v_mad_i64_i32 v[132:133], s[2:3], v132, s33, v[128:129]
	s_waitcnt lgkmcnt(0)
	v_mul_f32_e32 v134, v44, v136
	v_mul_f32_e32 v135, 0xbfb8aa3b, v134
	v_exp_f32_e32 v135, v135
	s_nop 0
	v_add_f32_e32 v135, 1.0, v135
	v_rcp_f32_e32 v135, v135
	s_nop 0
	v_mul_f32_e32 v134, v134, v135
	v_mul_f32_e32 v135, v40, v136
	v_mul_f32_e32 v134, v135, v134
	v_mul_f32_e32 v135, v45, v136
	v_mul_f32_e32 v137, 0xbfb8aa3b, v135
	v_exp_f32_e32 v137, v137
	s_nop 0
	v_add_f32_e32 v137, 1.0, v137
	v_rcp_f32_e32 v137, v137
	s_nop 0
	v_mul_f32_e32 v135, v135, v137
	v_mul_f32_e32 v137, v41, v136
	v_mul_f32_e32 v135, v137, v135
	v_mul_f32_e32 v137, v46, v136
	v_mul_f32_e32 v138, 0xbfb8aa3b, v137
	v_exp_f32_e32 v138, v138
	v_cvt_pk_bf16_f32 v134, v134, v135
	s_nop 0
	v_add_f32_e32 v138, 1.0, v138
	v_rcp_f32_e32 v138, v138
	s_nop 0
	v_mul_f32_e32 v137, v137, v138
	v_mul_f32_e32 v138, v42, v136
	v_mul_f32_e32 v137, v138, v137
	v_mul_f32_e32 v138, v47, v136
	v_mul_f32_e32 v139, 0xbfb8aa3b, v138
	v_exp_f32_e32 v139, v139
	s_nop 0
	v_add_f32_e32 v139, 1.0, v139
	v_rcp_f32_e32 v139, v139
	s_nop 0
	v_mul_f32_e32 v138, v138, v139
	v_mul_f32_e32 v139, v43, v136
	v_mul_f32_e32 v138, v139, v138
	v_cvt_pk_bf16_f32 v135, v137, v138
	v_mov_b32_e32 v248, v134
	v_mov_b32_e32 v249, v135
	v_mul_f32_e32 v134, v36, v136
	v_mul_f32_e32 v135, 0xbfb8aa3b, v134
	v_exp_f32_e32 v135, v135
	s_nop 0
	v_add_f32_e32 v135, 1.0, v135
	v_rcp_f32_e32 v135, v135
	s_nop 0
	v_mul_f32_e32 v134, v134, v135
	v_mul_f32_e32 v135, v32, v136
	v_mul_f32_e32 v134, v135, v134
	v_mul_f32_e32 v135, v37, v136
	v_mul_f32_e32 v137, 0xbfb8aa3b, v135
	v_exp_f32_e32 v137, v137
	s_nop 0
	v_add_f32_e32 v137, 1.0, v137
	v_rcp_f32_e32 v137, v137
	s_nop 0
	v_mul_f32_e32 v135, v135, v137
	v_mul_f32_e32 v137, v33, v136
	v_mul_f32_e32 v135, v137, v135
	v_mul_f32_e32 v137, v38, v136
	v_mul_f32_e32 v138, 0xbfb8aa3b, v137
	v_exp_f32_e32 v138, v138
	v_cvt_pk_bf16_f32 v134, v134, v135
	s_nop 0
	v_add_f32_e32 v138, 1.0, v138
	v_rcp_f32_e32 v138, v138
	s_nop 0
	v_mul_f32_e32 v137, v137, v138
	v_mul_f32_e32 v138, v34, v136
	v_mul_f32_e32 v137, v138, v137
	v_mul_f32_e32 v138, v39, v136
	v_mul_f32_e32 v139, 0xbfb8aa3b, v138
	v_exp_f32_e32 v139, v139
	v_mul_f32_e32 v136, v35, v136
	v_add_f32_e32 v139, 1.0, v139
	v_rcp_f32_e32 v139, v139
	s_nop 0
	v_mul_f32_e32 v138, v138, v139
	v_mul_f32_e32 v136, v136, v138
	v_cvt_pk_bf16_f32 v135, v137, v136
	v_mov_b32_e32 v250, v134
	v_mov_b32_e32 v251, v135
	s_nop 1
	v_permlane16_swap_b32 v248, v250
	v_permlane16_swap_b32 v249, v251
	flat_store_dwordx4 v[132:133], v[248:251]
	ds_read_b32 v136, v130 offset:384
	v_or_b32_e32 v132, 0x60, v131
	v_mad_i64_i32 v[132:133], s[2:3], v132, s33, v[128:129]
	v_or_b32_e32 v131, 0x70, v131
	s_waitcnt lgkmcnt(0)
	v_mul_f32_e32 v134, v28, v136
	v_mul_f32_e32 v135, 0xbfb8aa3b, v134
	v_exp_f32_e32 v135, v135
	v_mad_i64_i32 v[128:129], s[2:3], v131, s33, v[128:129]
	v_add_f32_e32 v135, 1.0, v135
	v_rcp_f32_e32 v135, v135
	s_nop 0
	v_mul_f32_e32 v134, v134, v135
	v_mul_f32_e32 v135, v24, v136
	v_mul_f32_e32 v134, v135, v134
	v_mul_f32_e32 v135, v29, v136
	v_mul_f32_e32 v137, 0xbfb8aa3b, v135
	v_exp_f32_e32 v137, v137
	s_nop 0
	v_add_f32_e32 v137, 1.0, v137
	v_rcp_f32_e32 v137, v137
	s_nop 0
	v_mul_f32_e32 v135, v135, v137
	v_mul_f32_e32 v137, v25, v136
	v_mul_f32_e32 v135, v137, v135
	v_mul_f32_e32 v137, v30, v136
	v_mul_f32_e32 v138, 0xbfb8aa3b, v137
	v_exp_f32_e32 v138, v138
	v_cvt_pk_bf16_f32 v134, v134, v135
	s_nop 0
	v_add_f32_e32 v138, 1.0, v138
	v_rcp_f32_e32 v138, v138
	s_nop 0
	v_mul_f32_e32 v137, v137, v138
	v_mul_f32_e32 v138, v26, v136
	v_mul_f32_e32 v137, v138, v137
	v_mul_f32_e32 v138, v31, v136
	v_mul_f32_e32 v139, 0xbfb8aa3b, v138
	v_exp_f32_e32 v139, v139
	s_nop 0
	v_add_f32_e32 v139, 1.0, v139
	v_rcp_f32_e32 v139, v139
	s_nop 0
	v_mul_f32_e32 v138, v138, v139
	v_mul_f32_e32 v139, v27, v136
	v_mul_f32_e32 v138, v139, v138
	v_cvt_pk_bf16_f32 v135, v137, v138
	v_mov_b32_e32 v248, v134
	v_mov_b32_e32 v249, v135
	v_mul_f32_e32 v134, v20, v136
	v_mul_f32_e32 v135, 0xbfb8aa3b, v134
	v_exp_f32_e32 v135, v135
	s_nop 0
	v_add_f32_e32 v135, 1.0, v135
	v_rcp_f32_e32 v135, v135
	s_nop 0
	v_mul_f32_e32 v134, v134, v135
	v_mul_f32_e32 v135, v16, v136
	v_mul_f32_e32 v134, v135, v134
	v_mul_f32_e32 v135, v21, v136
	v_mul_f32_e32 v137, 0xbfb8aa3b, v135
	v_exp_f32_e32 v137, v137
	s_nop 0
	v_add_f32_e32 v137, 1.0, v137
	v_rcp_f32_e32 v137, v137
	s_nop 0
	v_mul_f32_e32 v135, v135, v137
	v_mul_f32_e32 v137, v17, v136
	v_mul_f32_e32 v135, v137, v135
	v_mul_f32_e32 v137, v22, v136
	v_mul_f32_e32 v138, 0xbfb8aa3b, v137
	v_exp_f32_e32 v138, v138
	v_cvt_pk_bf16_f32 v134, v134, v135
	s_nop 0
	v_add_f32_e32 v138, 1.0, v138
	v_rcp_f32_e32 v138, v138
	s_nop 0
	v_mul_f32_e32 v137, v137, v138
	v_mul_f32_e32 v138, v18, v136
	v_mul_f32_e32 v137, v138, v137
	v_mul_f32_e32 v138, v23, v136
	v_mul_f32_e32 v139, 0xbfb8aa3b, v138
	v_exp_f32_e32 v139, v139
	v_mul_f32_e32 v136, v19, v136
	v_add_f32_e32 v139, 1.0, v139
	v_rcp_f32_e32 v139, v139
	s_nop 0
	v_mul_f32_e32 v138, v138, v139
	v_mul_f32_e32 v136, v136, v138
	v_cvt_pk_bf16_f32 v135, v137, v136
	v_mov_b32_e32 v250, v134
	v_mov_b32_e32 v251, v135
	s_nop 1
	v_permlane16_swap_b32 v248, v250
	v_permlane16_swap_b32 v249, v251
	flat_store_dwordx4 v[132:133], v[248:251]
	ds_read_b32 v132, v130 offset:448
	s_waitcnt lgkmcnt(0)
	v_mul_f32_e32 v130, v12, v132
	v_mul_f32_e32 v131, 0xbfb8aa3b, v130
	v_exp_f32_e32 v131, v131
	s_nop 0
	v_add_f32_e32 v131, 1.0, v131
	v_rcp_f32_e32 v131, v131
	s_nop 0
	v_mul_f32_e32 v130, v130, v131
	v_mul_f32_e32 v131, v8, v132
	v_mul_f32_e32 v130, v131, v130
	v_mul_f32_e32 v131, v13, v132
	v_mul_f32_e32 v133, 0xbfb8aa3b, v131
	v_exp_f32_e32 v133, v133
	s_nop 0
	v_add_f32_e32 v133, 1.0, v133
	v_rcp_f32_e32 v133, v133
	s_nop 0
	v_mul_f32_e32 v131, v131, v133
	v_mul_f32_e32 v133, v9, v132
	v_mul_f32_e32 v131, v133, v131
	v_mul_f32_e32 v133, v14, v132
	v_mul_f32_e32 v134, 0xbfb8aa3b, v133
	v_exp_f32_e32 v134, v134
	v_cvt_pk_bf16_f32 v130, v130, v131
	s_nop 0
	v_add_f32_e32 v134, 1.0, v134
	v_rcp_f32_e32 v134, v134
	s_nop 0
	v_mul_f32_e32 v133, v133, v134
	v_mul_f32_e32 v134, v10, v132
	v_mul_f32_e32 v133, v134, v133
	v_mul_f32_e32 v134, v15, v132
	v_mul_f32_e32 v135, 0xbfb8aa3b, v134
	v_exp_f32_e32 v135, v135
	s_nop 0
	v_add_f32_e32 v135, 1.0, v135
	v_rcp_f32_e32 v135, v135
	s_nop 0
	v_mul_f32_e32 v134, v134, v135
	v_mul_f32_e32 v135, v11, v132
	v_mul_f32_e32 v134, v135, v134
	v_cvt_pk_bf16_f32 v131, v133, v134
	v_mov_b32_e32 v248, v130
	v_mov_b32_e32 v249, v131
	v_mul_f32_e32 v130, v4, v132
	v_mul_f32_e32 v131, 0xbfb8aa3b, v130
	v_exp_f32_e32 v131, v131
	s_nop 0
	v_add_f32_e32 v131, 1.0, v131
	v_rcp_f32_e32 v131, v131
	s_nop 0
	v_mul_f32_e32 v130, v130, v131
	v_mul_f32_e32 v131, v0, v132
	v_mul_f32_e32 v130, v131, v130
	v_mul_f32_e32 v131, v5, v132
	v_mul_f32_e32 v133, 0xbfb8aa3b, v131
	v_exp_f32_e32 v133, v133
	s_nop 0
	v_add_f32_e32 v133, 1.0, v133
	v_rcp_f32_e32 v133, v133
	s_nop 0
	v_mul_f32_e32 v131, v131, v133
	v_mul_f32_e32 v133, v1, v132
	v_mul_f32_e32 v131, v133, v131
	v_mul_f32_e32 v133, v6, v132
	v_mul_f32_e32 v134, 0xbfb8aa3b, v133
	v_exp_f32_e32 v134, v134
	v_cvt_pk_bf16_f32 v130, v130, v131
	s_nop 0
	v_add_f32_e32 v134, 1.0, v134
	v_rcp_f32_e32 v134, v134
	s_nop 0
	v_mul_f32_e32 v133, v133, v134
	v_mul_f32_e32 v134, v2, v132
	v_mul_f32_e32 v133, v134, v133
	v_mul_f32_e32 v134, v7, v132
	v_mul_f32_e32 v135, 0xbfb8aa3b, v134
	v_exp_f32_e32 v135, v135
	v_mul_f32_e32 v132, v3, v132
	v_add_f32_e32 v135, 1.0, v135
	v_rcp_f32_e32 v135, v135
	s_nop 0
	v_mul_f32_e32 v134, v134, v135
	v_mul_f32_e32 v132, v132, v134
	v_cvt_pk_bf16_f32 v131, v133, v132
	v_mov_b32_e32 v250, v130
	v_mov_b32_e32 v251, v131
	s_nop 1
	v_permlane16_swap_b32 v248, v250
	v_permlane16_swap_b32 v249, v251
	flat_store_dwordx4 v[128:129], v[248:251]
	s_cbranch_execnz .LBB0_653
	s_branch .LBB0_676
